# v24 + index phase: next-tile mma burst (window + mask passes) merged with the following relu-sum block: 4 K reads issued together into free VGPRs, MFMAs spread through the VALU
# speedup vs baseline: 1.0031x; 1.0020x over previous
; DI float xhalf_sum(float v) { const auto r = __builtin_amdgcn_permlane32_swap(__float_as_uint(v), __float_as_uint(v), false, false); return __uint_as_float(r[0]) + __uint_as_float(r[1]); }
; DI void phase_index(const Params& p, unsigned char* lds) {
;     ...
;         auto proc = [&](auto PASSC, auto DIAGC, const f32x16& s, int k0, int kb) {
;             constexpr int PASS = decltype(PASSC)::value; constexpr bool DIAG = decltype(DIAGC)::value != 0;
;             f32x4 tot;
; #pragma unroll
;             for (int q = 0; q < 4; ++q) {
;                 float pr = 0.f;
; #pragma unroll
;                 for (int e = 0; e < 4; ++e) pr += wq[q][e] * fmaxf(s[4 * q + e], 0.f);
;                 tot[q] = xhalf_sum(pr);
;             }
;     ...
;                     if (sub + 1 < nsub) mma(sA, toff + 9216);
;                     if (kt == nt - 1) proc(PASSC, IC<1>{}, sB, k0, 1); else proc(PASSC, IC<0>{}, sB, k0, 1);
.LBB0_2638:
	v_add_u32_e32 v228, 0x12400, v168
	v_add_u32_e32 v229, 0x12420, v168
	v_add_u32_e32 v230, 0x12440, v168
	v_add_u32_e32 v231, 0x12460, v168
	ds_read_b128 v[212:215], v228
	ds_read_b128 v[216:219], v229
	ds_read_b128 v[220:223], v230
	ds_read_b128 v[224:227], v231
	v_max_f32_e32 v18, 0, v18
	v_fma_f32 v168, v50, v18, 0
	v_max_f32_e32 v18, 0, v19
	v_fmac_f32_e32 v168, v51, v18
	v_max_f32_e32 v18, 0, v20
	v_fmac_f32_e32 v168, v52, v18
	v_max_f32_e32 v18, 0, v21
	v_fmac_f32_e32 v168, v53, v18
	v_max_f32_e32 v18, 0, v22
	v_fma_f32 v18, v54, v18, 0
	v_max_f32_e32 v19, 0, v23
	v_fmac_f32_e32 v18, v55, v19
	v_max_f32_e32 v19, 0, v24
	v_fmac_f32_e32 v18, v56, v19
	s_waitcnt lgkmcnt(3)
	v_mfma_f32_32x32x16_bf16 v[2:17], v[42:45], v[212:215], 0
	v_max_f32_e32 v19, 0, v25
	v_fmac_f32_e32 v18, v57, v19
	v_max_f32_e32 v19, 0, v26
	v_fma_f32 v20, v58, v19, 0
	v_max_f32_e32 v19, 0, v27
	v_fmac_f32_e32 v20, v59, v19
	s_waitcnt lgkmcnt(2)
	v_mfma_f32_32x32x16_bf16 v[2:17], v[34:37], v[216:219], v[2:17]
	v_max_f32_e32 v19, 0, v28
	v_fmac_f32_e32 v20, v60, v19
	v_max_f32_e32 v19, 0, v29
	v_fmac_f32_e32 v20, v61, v19
	v_max_f32_e32 v19, 0, v30
	v_fma_f32 v19, v62, v19, 0
	s_waitcnt lgkmcnt(1)
	v_mfma_f32_32x32x16_bf16 v[2:17], v[38:41], v[220:223], v[2:17]
	v_max_f32_e32 v21, 0, v31
	v_fmac_f32_e32 v19, v63, v21
	v_max_f32_e32 v21, 0, v32
	v_fmac_f32_e32 v19, v64, v21
	v_max_f32_e32 v21, 0, v33
	v_fmac_f32_e32 v19, v65, v21
	s_waitcnt lgkmcnt(0)
	v_mfma_f32_32x32x16_bf16 v[2:17], v[46:49], v[224:227], v[2:17]
	s_branch .Lidx_il_w_cont

; DI void phase_index(const Params& p, unsigned char* lds) {
;     ...
;             const int key = k0 + 32 * kb + r32;
; #pragma unroll
;             for (int qq = 0; qq < 2; ++qq) {
;                 const float t_lo = tot[qq], t_hi = tot[2 + qq];
;                 const float sc = ((lane & 32) ? t_hi : t_lo) + 0.0f;
;                 const unsigned ub = __float_as_uint(sc);
;                 const unsigned uk = ub ^ ((unsigned)((int)ub >> 31) | 0x80000000u);
;                 const bool valid = DIAG ? (key <= tq0 + qq) : true;
;                 if (PASS == 0) {
;                     if (valid) { const unsigned a = (uk >> 21) & 0x7feu; atomicAdd((unsigned*)(lds + hbase0 + qq * 2048 + (a & ~3u)), 1u << ((a & 2u) << 3)); }
;                 } else if (PASS == 1) {
;                     if (valid && (int)(uk >> 22) == b1v[qq]) { const unsigned a = (uk >> 11) & 0x7feu; atomicAdd((unsigned*)(lds + hbase0 + qq * 2048 + (a & ~3u)), 1u << ((a & 2u) << 3)); }
;                 } else if (PASS == 3) {
;                     if (valid) {
;                         const int k10 = (int)(uk >> 22), d = k10 - b1v[qq];
;                         if (k10 > hiv[qq]) cntA[qq] += 1;
;                         else if (d >= 0) {
;                             const unsigned bin = ((unsigned)d << sbv[qq]) | ((uk >> (22 - sbv[qq])) & ((1u << sbv[qq]) - 1u));
;                             const unsigned a = bin << 1;
;                             atomicAdd((unsigned*)(lds + hbase0 + qq * 2048 + (a & ~3u)), 1u << ((a & 2u) << 3));
;                         }
;                     }
.Lidx_il_w_cont:
	s_mov_b64 s[30:31], -1
	s_and_b64 vcc, exec, s[28:29]
	s_cbranch_vccz .LBB0_2653
	v_mov_b32_e32 v21, v168
	v_mov_b32_e32 v22, v168
	v_mov_b32_e32 v23, v20
	v_mov_b32_e32 v24, v20
	v_permlane32_swap_b32_e32 v21, v22
	s_nop 0
	v_permlane32_swap_b32_e32 v23, v24
	v_add_f32_e32 v25, v21, v22
	v_add_f32_e32 v26, v23, v24
	v_cndmask_b32_e64 v25, v26, v25, s[4:5]
	v_add_f32_e32 v25, 0, v25
	v_ashrrev_i32_e32 v26, 31, v25
	v_bitop3_b32 v25, v26, v25, s82 bitop3:0x36
	v_mov_b32_e32 v21, v18
	v_mov_b32_e32 v22, v18
	v_mov_b32_e32 v23, v19
	v_mov_b32_e32 v24, v19
	v_lshrrev_b32_e32 v26, 22, v25
	v_permlane32_swap_b32_e32 v21, v22
	v_permlane32_swap_b32_e32 v23, v24
	v_cmp_le_i32_e32 vcc, v26, v101
	s_and_saveexec_b64 s[28:29], vcc
	s_xor_b64 s[28:29], exec, s[28:29]
	s_cbranch_execz .LBB0_2644
	v_sub_u32_e32 v26, v26, v100
	v_cmp_lt_i32_e32 vcc, -1, v26
	s_and_saveexec_b64 s[30:31], vcc
	s_cbranch_execz .LBB0_2643
	v_lshrrev_b32_e32 v25, v113, v25
	v_and_b32_e32 v25, v25, v114
	v_lshl_or_b32 v25, v26, v111, v25
	v_lshlrev_b32_e32 v26, 1, v25
	v_and_b32_e32 v26, -4, v26
	v_lshlrev_b32_e32 v25, 4, v25
	v_add_u32_e32 v26, v123, v26
	v_lshlrev_b32_e64 v25, v25, 1
	ds_add_u32 v26, v25

; DI float xhalf_sum(float v) { const auto r = __builtin_amdgcn_permlane32_swap(__float_as_uint(v), __float_as_uint(v), false, false); return __uint_as_float(r[0]) + __uint_as_float(r[1]); }
; DI void phase_index(const Params& p, unsigned char* lds) {
;     ...
;         auto proc = [&](auto PASSC, auto DIAGC, const f32x16& s, int k0, int kb) {
;             constexpr int PASS = decltype(PASSC)::value; constexpr bool DIAG = decltype(DIAGC)::value != 0;
;             f32x4 tot;
; #pragma unroll
;             for (int q = 0; q < 4; ++q) {
;                 float pr = 0.f;
; #pragma unroll
;                 for (int e = 0; e < 4; ++e) pr += wq[q][e] * fmaxf(s[4 * q + e], 0.f);
;                 tot[q] = xhalf_sum(pr);
;             }
;     ...
;                     if (sub + 1 < nsub) mma(sA, toff + 9216);
;                     if (kt == nt - 1) proc(PASSC, IC<1>{}, sB, k0, 1); else proc(PASSC, IC<0>{}, sB, k0, 1);
.LBB0_3523:
	ds_read_b128 v[212:215], v163 offset:9216
	ds_read_b128 v[216:219], v163 offset:9248
	ds_read_b128 v[220:223], v163 offset:9280
	ds_read_b128 v[224:227], v163 offset:9312
	v_max_f32_e32 v18, 0, v18
	v_fma_f32 v18, v50, v18, 0
	v_max_f32_e32 v19, 0, v19
	v_fmac_f32_e32 v18, v51, v19
	v_max_f32_e32 v19, 0, v20
	v_fmac_f32_e32 v18, v52, v19
	v_max_f32_e32 v19, 0, v21
	v_fmac_f32_e32 v18, v53, v19
	v_max_f32_e32 v19, 0, v22
	v_fma_f32 v19, v54, v19, 0
	v_max_f32_e32 v20, 0, v23
	v_fmac_f32_e32 v19, v55, v20
	v_max_f32_e32 v20, 0, v24
	v_fmac_f32_e32 v19, v56, v20
	s_waitcnt lgkmcnt(3)
	v_mfma_f32_32x32x16_bf16 v[2:17], v[42:45], v[212:215], 0
	v_max_f32_e32 v20, 0, v25
	v_fmac_f32_e32 v19, v57, v20
	v_max_f32_e32 v20, 0, v26
	v_fma_f32 v20, v58, v20, 0
	v_max_f32_e32 v21, 0, v27
	v_fmac_f32_e32 v20, v59, v21
	s_waitcnt lgkmcnt(2)
	v_mfma_f32_32x32x16_bf16 v[2:17], v[34:37], v[216:219], v[2:17]
	v_max_f32_e32 v21, 0, v28
	v_fmac_f32_e32 v20, v60, v21
	v_max_f32_e32 v21, 0, v29
	v_fmac_f32_e32 v20, v61, v21
	v_max_f32_e32 v21, 0, v30
	v_fma_f32 v21, v62, v21, 0
	s_waitcnt lgkmcnt(1)
	v_mfma_f32_32x32x16_bf16 v[2:17], v[38:41], v[220:223], v[2:17]
	v_max_f32_e32 v22, 0, v31
	v_fmac_f32_e32 v21, v63, v22
	v_max_f32_e32 v22, 0, v32
	v_fmac_f32_e32 v21, v64, v22
	v_max_f32_e32 v22, 0, v33
	v_fmac_f32_e32 v21, v65, v22
	s_waitcnt lgkmcnt(0)
	v_mfma_f32_32x32x16_bf16 v[2:17], v[46:49], v[224:227], v[2:17]
	s_branch .Lidx_il_m_cont

; DI void phase_index(const Params& p, unsigned char* lds) {
;     ...
;                 } else {
;                     const int k20 = (int)(uk >> kshv[qq]);
;                     const u64 bg = __ballot(valid && k20 > tauv[qq]);
;                     const u64 be = __ballot(valid && k20 == tauv[qq]);
;                     Gm[qq] |= (bg & 0xffffffffull) << (32 * kb); Gm[2 + qq] |= (bg >> 32) << (32 * kb);
;                     Em[qq] |= (be & 0xffffffffull) << (32 * kb); Em[2 + qq] |= (be >> 32) << (32 * kb);
;                 }
.Lidx_il_m_cont:
	s_mov_b64 s[28:29], -1
	s_and_b64 vcc, exec, s[58:59]
	s_cbranch_vccz .LBB0_3526
	v_mov_b32_e32 v22, v18
	v_mov_b32_e32 v24, v18
	v_mov_b32_e32 v23, v19
	v_mov_b32_e32 v25, v19
	v_mov_b32_e32 v26, v20
	v_mov_b32_e32 v28, v20
	v_mov_b32_e32 v27, v21
	v_mov_b32_e32 v29, v21
	v_permlane32_swap_b32_e32 v22, v24
	v_permlane32_swap_b32_e32 v23, v25
	v_permlane32_swap_b32_e32 v26, v28
	v_permlane32_swap_b32_e32 v27, v29
	v_pk_add_f32 v[22:23], v[22:23], v[24:25]
	v_pk_add_f32 v[24:25], v[26:27], v[28:29]
	s_mov_b64 s[28:29], 0
	v_cndmask_b32_e64 v23, v25, v23, s[4:5]
	v_cndmask_b32_e64 v22, v24, v22, s[4:5]
	v_pk_add_f32 v[22:23], v[22:23], 0 op_sel_hi:[1,0]
	s_nop 0
	v_ashrrev_i32_e32 v24, 31, v23
	v_ashrrev_i32_e32 v25, 31, v22
	v_or_b32_e32 v24, 0x80000000, v24
	v_or_b32_e32 v25, 0x80000000, v25
	v_xor_b32_e32 v23, v24, v23
	v_xor_b32_e32 v22, v25, v22
	v_lshrrev_b32_e32 v23, v83, v23
	v_lshrrev_b32_e32 v22, v106, v22
	v_cmp_gt_i32_e64 s[58:59], v22, v100
	v_cmp_eq_u32_e64 s[68:69], v22, v100
	v_cmp_gt_i32_e64 s[30:31], v23, v1
	v_cmp_eq_u32_e64 s[26:27], v23, v1
